# work-queue next-item prefetch (atomic issued one item ahead)
# speedup vs baseline: 1.1274x; 1.0068x over previous
; __global__ void __launch_bounds__(512, 2) mega_fwd(Args args) {
;     ...
;             for (;;) {
;                 __syncthreads();
;                 if (tid == 0) *(volatile int*)(lds + 147712) = (int)atomicAdd(ctl + 64 * b, 1u);
;                 __syncthreads();
;                 const int item = *(volatile int*)(lds + 147712);
;                 if (item >= T / 4) break;
;                 attn_item(P, lds, b, 4 * ((T / 4 - 1) - item), tid);
.Lq_next:
	s_waitcnt vmcnt(32)
	s_mov_b64 s[12:13], exec
	s_and_b64 exec, exec, s[0:1]
	v_mov_b32_e32 v0, 0x24104
	ds_write_b32 v0, v254
	s_mov_b64 exec, s[12:13]
	v_mov_b32_e32 v0, 0x24104
	s_waitcnt lgkmcnt(0)
	s_barrier
	ds_read_b32 v0, v0
	s_waitcnt lgkmcnt(0)
	s_branch .Lq_have_item
	s_nop 0
	s_nop 0
	s_nop 0
	s_nop 0
	s_nop 0
	s_nop 0

; #define TILE_LOAD(SLOT, CC, TT) do { const bf16_t* kp = P.KI + (rowb + 64 * (CC) + 16 * (TT) + r16) * 64 + 8 * g; Bk[SLOT][0] = *(const bf16x8*)kp; Bk[SLOT][1] = *(const bf16x8*)(kp + 32); } while (0)
; __device__ __forceinline__ void attn_item(const Ptrs& P, unsigned char* lds, int b, int tq0, int tid) {
;     ...
;     const int tmax = tq0 + 3;
;     if (tmax < 256 || (DBG & 4)) {
;         for (int i = tid; i < 1024; i += 512) sel[i] = (unsigned short)(((i & 255) <= tq0 + (i >> 8)) ? (i & 255) : 0);
;         __syncthreads();
;     } else {
;         bf16x8 Aq[4][2]; f32x4 wq[4];
; #pragma unroll
;         for (int q = 0; q < 4; ++q) { const bf16_t* qp = P.QI + (rowb + tq0 + q) * 1024 + r16 * 64 + 8 * g; Aq[q][0] = *(const bf16x8*)qp; Aq[q][1] = *(const bf16x8*)(qp + 32);
;             wq[q] = *(const f32x4*)(P.WI + (rowb + tq0 + q) * 16 + 4 * g); }
;         unsigned* KB = (unsigned*)lds;
;         const int nch = (tmax >> 6) + 1;
;         const int ni = (w < nch) ? ((nch - w + 7) >> 3) : 0;
;         bf16x8 Bk[4][2];
;     ...
;         if (ni > 0) { TILE_LOAD(0, w, 0); TILE_LOAD(1, w, 1); }
.Lq_have_item:
	s_movk_i32 s12, 0x800
	s_waitcnt lgkmcnt(0)
	v_cmp_gt_i32_e32 vcc, s12, v0
	s_mov_b64 s[12:13], -1
	s_and_saveexec_b64 s[70:71], vcc
	s_cbranch_execz .LBB0_465
	v_lshlrev_b32_e32 v64, 2, v0
	v_sub_u32_e32 v124, 0x1ffc, v64
	v_readfirstlane_b32 s63, v188
	s_movk_i32 s12, 0xfc
	s_lshr_b32 s62, s63, 6
	v_cmp_lt_u32_e32 vcc, s12, v124
	s_and_saveexec_b64 s[12:13], vcc
	s_xor_b64 s[60:61], exec, s[12:13]
	s_cbranch_execz .LBB0_913
	v_sub_u32_e32 v126, 0x1fff, v64
	v_lshrrev_b32_e32 v125, 6, v126
	v_subrev_u32_e32 v0, s62, v125
	v_add_u32_e32 v65, 8, v0
	v_cmp_le_u32_e32 vcc, s62, v125
	v_cmp_lt_u32_e64 s[12:13], 7, v65
	s_and_b64 s[14:15], vcc, s[12:13]
	s_and_saveexec_b64 s[12:13], s[14:15]
	s_cbranch_execz .LBB0_479
	s_and_b32 s14, s63, 0xffffffc0
	v_add_u32_e32 v164, s81, v124
	s_ashr_i32 s15, s14, 31
	v_or_b32_e32 v40, 1, v164
	v_mov_b32_e32 v41, v165
	v_or_b32_e32 v32, 2, v164
	v_mov_b32_e32 v33, v165
	v_or_b32_e32 v34, 3, v164
	v_mov_b32_e32 v35, v165
	v_lshl_add_u64 v[48:49], s[14:15], 0, v[182:183]
	v_lshlrev_b64 v[0:1], 11, v[164:165]
	v_lshlrev_b64 v[8:9], 11, v[40:41]
	v_lshlrev_b64 v[16:17], 11, v[32:33]
	v_lshlrev_b64 v[24:25], 11, v[34:35]
	v_lshlrev_b64 v[34:35], 6, v[34:35]
	v_lshlrev_b64 v[32:33], 6, v[32:33]
	v_lshlrev_b64 v[40:41], 6, v[40:41]
	v_lshlrev_b64 v[42:43], 6, v[164:165]
	v_lshlrev_b64 v[48:49], 7, v[48:49]
	v_lshl_add_u64 v[4:5], v[168:169], 0, v[0:1]
	v_lshl_add_u64 v[12:13], v[168:169], 0, v[8:9]
	v_lshl_add_u64 v[20:21], v[168:169], 0, v[16:17]
	v_lshl_add_u64 v[28:29], v[168:169], 0, v[24:25]
	v_lshl_add_u64 v[34:35], v[170:171], 0, v[34:35]
	v_lshl_add_u64 v[36:37], v[170:171], 0, v[32:33]
	v_lshl_add_u64 v[40:41], v[170:171], 0, v[40:41]
	v_lshl_add_u64 v[44:45], v[170:171], 0, v[42:43]
	v_lshl_add_u64 v[60:61], v[172:173], 0, v[48:49]
	global_load_dwordx4 v[0:3], v[4:5], off
	s_nop 0
	global_load_dwordx4 v[4:7], v[4:5], off offset:64
	s_nop 0
	global_load_dwordx4 v[8:11], v[12:13], off
	s_nop 0
	global_load_dwordx4 v[12:15], v[12:13], off offset:64
	s_nop 0
	global_load_dwordx4 v[16:19], v[20:21], off
	s_nop 0
	global_load_dwordx4 v[20:23], v[20:21], off offset:64
	s_nop 0
	global_load_dwordx4 v[24:27], v[28:29], off
	s_nop 0
	global_load_dwordx4 v[28:31], v[28:29], off offset:64
	s_nop 0
	global_load_dwordx4 v[32:35], v[34:35], off
	s_nop 0
	global_load_dwordx4 v[36:39], v[36:37], off
	s_nop 0
	global_load_dwordx4 v[40:43], v[40:41], off
	s_nop 0
	global_load_dwordx4 v[44:47], v[44:45], off
	s_nop 0
	v_lshrrev_b32_e32 v127, 3, v65
	v_sub_u32_e32 v128, 0x1ffd, v64
	v_sub_u32_e32 v129, 0x1ffe, v64
	v_mov_b64_e32 v[150:151], v[60:61]
	s_mov_b64 s[18:19], 0x1000
	v_lshl_add_u64 v[152:153], v[60:61], 0, s[18:19]
	global_load_dwordx4 v[48:51], v[150:151], off
	global_load_dwordx4 v[52:55], v[150:151], off offset:1024
	global_load_dwordx4 v[56:59], v[150:151], off offset:2048
	global_load_dwordx4 v[60:63], v[150:151], off offset:3072
	global_load_dwordx4 v[64:67], v[152:153], off
	global_load_dwordx4 v[68:71], v[152:153], off offset:1024
	global_load_dwordx4 v[72:75], v[152:153], off offset:2048
	global_load_dwordx4 v[76:79], v[152:153], off offset:3072
	s_mov_b64 s[18:19], 0x10000
	v_lshl_add_u64 v[150:151], v[150:151], 0, s[18:19]
	v_lshl_add_u64 v[152:153], v[152:153], 0, s[18:19]
	s_mov_b32 s20, 0
	v_lshl_add_u32 v130, s62, 8, v203
	v_add_u32_e32 v155, 0x10000, v130
	v_add_u32_e32 v154, s14, v179
	s_nop 0
	v_readfirstlane_b32 s14, v127

; __device__ __forceinline__ void attn_item(const Ptrs& P, unsigned char* lds, int b, int tq0, int tid) {
;     ...
;         const unsigned seq = (xw[32 + w] + 1u) & 0xffu; if (lane == 0) xw[32 + w] = seq;
; __global__ void __launch_bounds__(512, 2) mega_fwd(Args args) {
;     ...
;                 if (tid == 0) *(volatile int*)(lds + 147712) = (int)atomicAdd(ctl + 64 * b, 1u);
.LBB0_487:
	s_or_b64 exec, exec, s[12:13]
	s_lshl_b32 s83, s62, 2
	s_add_i32 s12, s83, 0
	s_add_i32 s20, s12, 0x24080
	v_mov_b64_e32 v[64:65], s[20:21]
	s_waitcnt lgkmcnt(0)
	s_barrier
	ds_read_b32 v64, v64
	s_waitcnt lgkmcnt(0)
	s_and_saveexec_b64 s[90:91], s[0:1]
	v_mov_b32_e32 v255, 1
	global_atomic_add v254, v165, v255, s[46:47] sc0
	s_mov_b64 exec, s[90:91]
	v_add_u32_e32 v64, 1, v64
	v_and_b32_e32 v96, 0xff, v64
	s_and_saveexec_b64 s[12:13], s[4:5]
	s_cbranch_execz .LBB0_489
	v_mov_b64_e32 v[64:65], s[20:21]
	ds_write_b32 v64, v96
	s_waitcnt lgkmcnt(0)

; #define PAIR_XCHG(SLOT, TAG, MINE, OTHER) do { const unsigned tg_ = (seq << 8) | (unsigned)(TAG); if (lane == 0) xw[w * 4 + (SLOT)] = ((MINE) << 16) | tg_; \
;             unsigned v_; do { v_ = xw[(w ^ 1) * 4 + (SLOT)]; } while ((v_ & 0xffffu) != tg_); OTHER = v_ >> 16; } while (0)
; __device__ __forceinline__ void attn_item(const Ptrs& P, unsigned char* lds, int b, int tq0, int tid) {
;     ...
;         const unsigned ig = wave_incl_scan(cg, lane), ie = wave_incl_scan(ce, lane);
;         const unsigned ngt = (unsigned)__builtin_amdgcn_readlane((int)ig, 63), neq = (unsigned)__builtin_amdgcn_readlane((int)ie, 63);
;         unsigned ogt, oeq;
;         PAIR_XCHG(2, 40, ngt, ogt); PAIR_XCHG(3, 41, neq, oeq);
.LBB0_511:
	s_or_b64 exec, exec, s[44:45]
	v_add_u32_dpp v24, v26, v26 row_shr:1 row_mask:0xf bank_mask:0xf bound_ctrl:1
	s_nop 1
	v_add_u32_dpp v24, v24, v24 row_shr:2 row_mask:0xf bank_mask:0xf bound_ctrl:1
	s_nop 1
	v_add_u32_dpp v24, v24, v24 row_shr:4 row_mask:0xf bank_mask:0xf bound_ctrl:1
	s_nop 1
	v_add_u32_dpp v24, v24, v24 row_shr:8 row_mask:0xf bank_mask:0xf bound_ctrl:1
	s_nop 0
	v_readlane_b32 s12, v24, 15
	v_readlane_b32 s13, v24, 31
	v_readlane_b32 s20, v24, 47
	v_mov_b32_e32 v27, s12
	v_cndmask_b32_e64 v27, v27, 0, s[6:7]
	v_add_u32_e32 v24, v27, v24
	v_mov_b32_e32 v27, s13
	v_mov_b32_e32 v29, s20
	v_cndmask_b32_e64 v27, 0, v27, s[8:9]
	v_cndmask_b32_e64 v29, 0, v29, s[10:11]
	v_add3_u32 v27, v24, v27, v29
	v_add_u32_dpp v24, v25, v25 row_shr:1 row_mask:0xf bank_mask:0xf bound_ctrl:1
	v_readlane_b32 s45, v27, 63
	s_nop 0
	v_add_u32_dpp v24, v24, v24 row_shr:2 row_mask:0xf bank_mask:0xf bound_ctrl:1
	s_nop 1
	v_add_u32_dpp v24, v24, v24 row_shr:4 row_mask:0xf bank_mask:0xf bound_ctrl:1
	s_nop 1
	v_add_u32_dpp v24, v24, v24 row_shr:8 row_mask:0xf bank_mask:0xf bound_ctrl:1
	s_nop 0
	v_readlane_b32 s12, v24, 15
	v_readlane_b32 s13, v24, 31
	v_readlane_b32 s20, v24, 47
	v_mov_b32_e32 v29, s12
	v_cndmask_b32_e64 v29, v29, 0, s[6:7]
	v_add_u32_e32 v24, v29, v24
	v_mov_b32_e32 v29, s13
	v_mov_b32_e32 v36, s20
	v_cndmask_b32_e64 v29, 0, v29, s[8:9]
	v_cndmask_b32_e64 v36, 0, v36, s[10:11]
	v_add3_u32 v29, v24, v29, v36
	v_or_b32_e32 v36, 40, v1
	v_readlane_b32 s44, v29, 63
	s_and_saveexec_b64 s[12:13], s[4:5]
	s_cbranch_execz .LBB0_513
	s_add_i32 s74, s74, 8
	v_lshl_or_b32 v24, s45, 16, v36
	v_mov_b32_e32 v38, s74
	v_mov_b32_e32 v39, s21
	ds_write_b32 v38, v24
	s_waitcnt lgkmcnt(0)

; #define PAIR_XCHG(SLOT, TAG, MINE, OTHER) do { const unsigned tg_ = (seq << 8) | (unsigned)(TAG); if (lane == 0) xw[w * 4 + (SLOT)] = ((MINE) << 16) | tg_; \
;             unsigned v_; do { v_ = xw[(w ^ 1) * 4 + (SLOT)]; } while ((v_ & 0xffffu) != tg_); OTHER = v_ >> 16; } while (0)
; __device__ __forceinline__ void attn_item(const Ptrs& P, unsigned char* lds, int b, int tq0, int tid) {
;     ...
;         PAIR_XCHG(2, 40, ngt, ogt); PAIR_XCHG(3, 41, neq, oeq);
.LBB0_514:
	v_mov_b64_e32 v[38:39], s[20:21]
	ds_read_b32 v24, v38
	s_waitcnt lgkmcnt(0)
	v_cmp_eq_u32_sdwa s[74:75], v24, v36 src0_sel:WORD_0 src1_sel:DWORD
	s_or_b64 s[12:13], s[74:75], s[12:13]
	s_andn2_b64 exec, exec, s[12:13]
	s_cbranch_execnz .LBB0_514
	s_or_b64 exec, exec, s[12:13]
	v_or_b32_e32 v36, 41, v1
	s_and_saveexec_b64 s[12:13], s[4:5]
	s_cbranch_execz .LBB0_517
	s_lshl_b32 s20, s83, 2
	s_add_i32 s20, s20, 0
	s_add_i32 s20, s20, 0x2400c
	v_lshl_or_b32 v37, s44, 16, v36
	v_mov_b32_e32 v38, s20
	v_mov_b32_e32 v39, s21
	ds_write_b32 v38, v37
	s_waitcnt lgkmcnt(0)

; #define PAIR_XCHG(SLOT, TAG, MINE, OTHER) do { const unsigned tg_ = (seq << 8) | (unsigned)(TAG); if (lane == 0) xw[w * 4 + (SLOT)] = ((MINE) << 16) | tg_; \
;             unsigned v_; do { v_ = xw[(w ^ 1) * 4 + (SLOT)]; } while ((v_ & 0xffffu) != tg_); OTHER = v_ >> 16; } while (0)
; __device__ __forceinline__ void attn_item(const Ptrs& P, unsigned char* lds, int b, int tq0, int tid) {
;     ...
;         PAIR_XCHG(2, 40, ngt, ogt); PAIR_XCHG(3, 41, neq, oeq);
;         const unsigned tot_gt = ngt + ogt, quota = 256u - tot_gt;
;         unsigned pos_g = (hs ? ogt : 0u) + ig - cg, pos_e = (hs ? oeq : 0u) + ie - ce;
;         const bool any_eq = (neq + oeq) != 0u;
; #pragma unroll
;         for (int k = 0; k < 4; ++k) if (16 * k < nact) {
; #pragma unroll
;             for (int r = 16 * k; r < 16 * k + 16; ++r) { const unsigned short idx = (unsigned short)(64 * (2 * r + hs) + lane);
;                 if (k2[r] > th) { sel[qs * 256 + pos_g] = idx; ++pos_g; }
;                 if (any_eq) { if (k2[r] == th) { if (pos_e < quota) sel[qs * 256 + tot_gt + pos_e] = idx; ++pos_e; } } } }
.LBB0_518:
	v_mov_b64_e32 v[38:39], s[20:21]
	ds_read_b32 v37, v38
	s_waitcnt lgkmcnt(0)
	v_cmp_eq_u32_sdwa s[74:75], v37, v36 src0_sel:WORD_0 src1_sel:DWORD
	s_or_b64 s[12:13], s[74:75], s[12:13]
	s_andn2_b64 exec, exec, s[12:13]
	s_cbranch_execnz .LBB0_518
	s_or_b64 exec, exec, s[12:13]
	s_cmp_eq_u32 s64, 0
	v_lshrrev_b32_e32 v36, 16, v24
	s_cselect_b64 s[12:13], -1, 0
	v_lshrrev_b32_e32 v37, 16, v37
	v_add_u32_e32 v38, s45, v36
	v_cndmask_b32_e64 v36, v36, 0, s[12:13]
	v_sub_u32_e32 v26, v27, v26
	v_add_u32_e32 v27, v36, v26
	v_cndmask_b32_e64 v26, v37, 0, s[12:13]
	v_sub_u32_e32 v25, v29, v25
	s_lshl_b32 s20, s65, 9
	v_add_u32_e32 v25, v26, v25
	v_sub_u32_e32 v26, 0, v37
	s_add_i32 s20, s20, 0
	v_cmp_ne_u32_e64 s[12:13], s44, v26
	s_lshl_b32 s44, s64, 6
	s_add_i32 s20, s20, 0x21000
	v_sub_u32_e32 v24, 0x100, v38
	v_lshl_add_u32 v26, v38, 1, s20
	v_or_b32_e32 v29, s44, v179
	s_and_saveexec_b64 s[74:75], s[18:19]
	s_cbranch_execz .LBB0_715
	v_cmp_gt_u32_e64 s[18:19], v6, v5
	s_and_saveexec_b64 s[44:45], s[18:19]
	v_lshl_add_u32 v36, v27, 1, s20
	v_add_u32_e32 v27, 1, v27
	ds_write_b16 v36, v29
	s_or_b64 exec, exec, s[44:45]
	v_cmp_eq_u32_e64 s[18:19], v6, v5
	s_and_b64 s[18:19], s[12:13], s[18:19]
	s_and_saveexec_b64 s[44:45], s[18:19]
	s_cbranch_execz .LBB0_526
	v_cmp_lt_u32_e64 s[18:19], v25, v24
	s_and_saveexec_b64 s[78:79], s[18:19]
	v_lshl_add_u32 v6, v25, 1, v26
	ds_write_b16 v6, v29
	s_or_b64 exec, exec, s[78:79]
	v_add_u32_e32 v25, 1, v25

; #define PAIR_XCHG(SLOT, TAG, MINE, OTHER) do { const unsigned tg_ = (seq << 8) | (unsigned)(TAG); if (lane == 0) xw[w * 4 + (SLOT)] = ((MINE) << 16) | tg_; \
;             unsigned v_; do { v_ = xw[(w ^ 1) * 4 + (SLOT)]; } while ((v_ & 0xffffu) != tg_); OTHER = v_ >> 16; } while (0)
; __device__ __forceinline__ void attn_item(const Ptrs& P, unsigned char* lds, int b, int tq0, int tid) {
;     ...
;         { unsigned dn_; PAIR_XCHG(0, 42, 0u, dn_); (void)dn_; }
.LBB0_908:
	s_or_b64 exec, exec, s[14:15]
	v_or_b32_e32 v0, 42, v1
	s_and_saveexec_b64 s[12:13], s[4:5]
	s_cbranch_execz .LBB0_910
	s_lshl_b32 s14, s83, 2
	s_add_i32 s14, s14, 0
	s_add_i32 s14, s14, 0x24008
	v_mov_b32_e32 v2, s14
	v_mov_b32_e32 v3, s21
	ds_write_b32 v2, v0
	s_waitcnt lgkmcnt(0)

; #define PAIR_XCHG(SLOT, TAG, MINE, OTHER) do { const unsigned tg_ = (seq << 8) | (unsigned)(TAG); if (lane == 0) xw[w * 4 + (SLOT)] = ((MINE) << 16) | tg_; \
;             unsigned v_; do { v_ = xw[(w ^ 1) * 4 + (SLOT)]; } while ((v_ & 0xffffu) != tg_); OTHER = v_ >> 16; } while (0)
; __device__ __forceinline__ void attn_item(const Ptrs& P, unsigned char* lds, int b, int tq0, int tid) {
;     ...
;     if (tmax < 256 || (DBG & 4)) {
;         for (int i = tid; i < 1024; i += 512) sel[i] = (unsigned short)(((i & 255) <= tq0 + (i >> 8)) ? (i & 255) : 0);
;         __syncthreads();
;     ...
;         { unsigned dn_; PAIR_XCHG(0, 42, 0u, dn_); (void)dn_; }
.LBB0_911:
	v_mov_b32_e32 v2, s73
	ds_read_b32 v1, v2
	s_waitcnt lgkmcnt(0)
	v_cmp_eq_u32_sdwa s[14:15], v1, v0 src0_sel:WORD_0 src1_sel:DWORD
	s_or_b64 s[12:13], s[14:15], s[12:13]
	s_andn2_b64 exec, exec, s[12:13]
	s_cbranch_execnz .LBB0_911
	s_or_b64 exec, exec, s[12:13]
.LBB0_913:
	s_or_saveexec_b64 s[14:15], s[60:61]
	v_mov_b32_e32 v32, s65
	v_mov_b32_e32 v219, s64
	s_xor_b64 exec, exec, s[14:15]
	s_cbranch_execz .LBB0_921
	s_and_saveexec_b64 s[90:91], s[0:1]
	v_mov_b32_e32 v255, 1
	global_atomic_add v254, v165, v255, s[46:47] sc0
	s_mov_b64 exec, s[90:91]
	v_sub_u32_e32 v0, v208, v64
	v_sub_u32_e32 v1, v210, v64
	s_mov_b32 s18, 0
	s_mov_b64 s[16:17], 0
	v_mov_b32_e32 v2, v209
	s_branch .LBB0_916

; __global__ void __launch_bounds__(512, 2) mega_fwd(Args args) {
	.amdhsa_kernel _Z8mega_fwd4Args
		.amdhsa_group_segment_fixed_size 12288
		.amdhsa_private_segment_fixed_size 0
		.amdhsa_kernarg_size 416
		.amdhsa_user_sgpr_count 2
		.amdhsa_user_sgpr_dispatch_ptr 0
		.amdhsa_user_sgpr_queue_ptr 0
		.amdhsa_user_sgpr_kernarg_segment_ptr 1
		.amdhsa_user_sgpr_dispatch_id 0
		.amdhsa_user_sgpr_kernarg_preload_length 0
		.amdhsa_user_sgpr_kernarg_preload_offset 0
		.amdhsa_user_sgpr_private_segment_size 0
		.amdhsa_uses_dynamic_stack 0
		.amdhsa_enable_private_segment 0
		.amdhsa_system_sgpr_workgroup_id_x 1
		.amdhsa_system_sgpr_workgroup_id_y 0
		.amdhsa_system_sgpr_workgroup_id_z 0
		.amdhsa_system_sgpr_workgroup_info 0
		.amdhsa_system_vgpr_workitem_id 2
		.amdhsa_next_free_vgpr 256
		.amdhsa_next_free_sgpr 98
		.amdhsa_accum_offset 256
		.amdhsa_reserve_vcc 1
		.amdhsa_float_round_mode_32 0
		.amdhsa_float_round_mode_16_64 0
		.amdhsa_float_denorm_mode_32 3
		.amdhsa_float_denorm_mode_16_64 3
		.amdhsa_dx10_clamp 1
		.amdhsa_ieee_mode 1
		.amdhsa_fp16_overflow 0
		.amdhsa_tg_split 0
		.amdhsa_exception_fp_ieee_invalid_op 0
		.amdhsa_exception_fp_denorm_src 0
		.amdhsa_exception_fp_ieee_div_zero 0
		.amdhsa_exception_fp_ieee_overflow 0
		.amdhsa_exception_fp_ieee_underflow 0
		.amdhsa_exception_fp_ieee_inexact 0
		.amdhsa_exception_int_div_zero 0
	.end_amdhsa_kernel

; __global__ void __launch_bounds__(512, 2) mega_fwd(Args args) {
amdhsa.kernels:
  - .agpr_count:     0
    .args:
      - .offset:         0
        .size:           160
        .value_kind:     by_value
      - .offset:         160
        .size:           4
        .value_kind:     hidden_block_count_x
      - .offset:         164
        .size:           4
        .value_kind:     hidden_block_count_y
      - .offset:         168
        .size:           4
        .value_kind:     hidden_block_count_z
      - .offset:         172
        .size:           2
        .value_kind:     hidden_group_size_x
      - .offset:         174
        .size:           2
        .value_kind:     hidden_group_size_y
      - .offset:         176
        .size:           2
        .value_kind:     hidden_group_size_z
      - .offset:         178
        .size:           2
        .value_kind:     hidden_remainder_x
      - .offset:         180
        .size:           2
        .value_kind:     hidden_remainder_y
      - .offset:         182
        .size:           2
        .value_kind:     hidden_remainder_z
      - .offset:         200
        .size:           8
        .value_kind:     hidden_global_offset_x
      - .offset:         208
        .size:           8
        .value_kind:     hidden_global_offset_y
      - .offset:         216
        .size:           8
        .value_kind:     hidden_global_offset_z
      - .offset:         224
        .size:           2
        .value_kind:     hidden_grid_dims
      - .offset:         248
        .size:           8
        .value_kind:     hidden_multigrid_sync_arg
      - .offset:         280
        .size:           4
        .value_kind:     hidden_dynamic_lds_size
    .group_segment_fixed_size: 12288
    .kernarg_segment_align: 8
    .kernarg_segment_size: 416
    .language:       OpenCL C
    .language_version:
      - 2
      - 0
    .max_flat_workgroup_size: 512
    .name:           _Z8mega_fwd4Args
    .private_segment_fixed_size: 0
    .sgpr_count:     104
    .sgpr_spill_count: 20
    .symbol:         _Z8mega_fwd4Args.kd
    .uniform_work_group_size: 1
    .uses_dynamic_stack: false
    .vgpr_count:     256
    .vgpr_spill_count: 0
    .wavefront_size: 64
